# down-proj epilogue: the eight row-partial loads issued together instead of load-wait-add one at a time
# speedup vs baseline: 1.0180x; 1.0180x over previous
;     __device__ __forceinline__ void operator()(const f32x4 (&acc)[2][2][4][2], const Unit& u, int wr, int wc, int fr, int fq) const {
;     ...
;         if (tid < 256) { float t = 0.f;
; #pragma unroll
;             for (int k = 0; k < 8; ++k) t += PART[((size_t)u.pm * 8 + k) * 256 + tid];
;             R[tid] = rsqrtf(t * (1.0f / DM) + 1e-6f); }
.LBB0_699:
	s_or_b64 exec, exec, s[12:13]
	s_barrier
	s_and_saveexec_b64 s[12:13], s[42:43]
	s_cbranch_execz .LBB0_701
	s_ashr_i32 s11, s10, 31
	s_lshl_b64 s[14:15], s[10:11], 13
	s_waitcnt lgkmcnt(0)
	v_lshl_add_u64 v[104:105], v[172:173], 0, s[14:15]
	global_load_dword v106, v[104:105], off
	global_load_dword v107, v[104:105], off offset:1024
	global_load_dword v244, v[104:105], off offset:2048
	global_load_dword v245, v[104:105], off offset:3072
	v_add_co_u32_e32 v104, vcc, 0x1000, v104
	s_nop 1
	v_addc_co_u32_e32 v105, vcc, 0, v105, vcc
	global_load_dword v246, v[104:105], off
	global_load_dword v247, v[104:105], off offset:1024
	global_load_dword v248, v[104:105], off offset:2048
	global_load_dword v249, v[104:105], off offset:3072
	s_waitcnt vmcnt(0)
	v_add_f32_e32 v106, 0, v106
	v_add_f32_e32 v106, v106, v107
	v_add_f32_e32 v106, v106, v244
	v_add_f32_e32 v106, v106, v245
	v_add_f32_e32 v106, v106, v246
	v_add_f32_e32 v106, v106, v247
	v_add_f32_e32 v106, v106, v248
	v_add_f32_e32 v104, v106, v249
	v_fmamk_f32 v104, v104, 0x3a000000, v231
	v_cmp_gt_f32_e32 vcc, s55, v104
	v_mul_f32_e32 v105, 0x4b800000, v104
	s_nop 0
	v_cndmask_b32_e32 v104, v104, v105, vcc
	v_rsq_f32_e32 v104, v104
	s_nop 0
	v_mul_f32_e32 v105, 0x45800000, v104
	v_cndmask_b32_e32 v104, v104, v105, vcc
	ds_write_b32 v210, v104
